# store/load tails widened: P4/P12 bf16 row stores merged to 16 bytes (v_permlane16_swap); P15 epilogue hand-written with 8 rows x 128 bytes per memory instruction (DPP row_ror:8 half exchange) and coun
# baseline (speedup 1.0000x reference)
; __device__ __forceinline__ int lane_asm() { int l; asm volatile("v_mbcnt_lo_u32_b32 %0, -1, 0\n\tv_mbcnt_hi_u32_b32 %0, -1, %0" : "=v"(l)); return l; }
;     __device__ __forceinline__ void operator()(const f32x4 (&acc)[2][2][4][2], const Unit& u, int wr, int wc, int fr_, int fq_) const {
;         const int l_ = lane_asm(); const int fr = l_ & 15, fq = l_ >> 4; (void)fr_; (void)fq_;
;         const int row0 = u.pm * BM + wr * 64 + fr, col0 = u.pn * BM + wc * 32 + 4 * fq;
;         f32x4 gv[2][2], gm[2][2];
; #pragma unroll
;         for (int bj = 0; bj < 2; ++bj)
; #pragma unroll
;             for (int n = 0; n < 2; ++n) { gv[bj][n] = *(const f32x4*)(gate + col0 + bj * HALF + n * 16);
;                 if constexpr (EMIT) gm[bj][n] = *(const f32x4*)(gmv + col0 + bj * HALF + n * 16); else gm[bj][n] = gv[bj][n]; }
; #pragma unroll
;         for (int ai = 0; ai < 2; ++ai)
; #pragma unroll
;         for (int mh = 0; mh < 2; ++mh) {
;             f32x4 bs[2][2][2];
; #pragma unroll
;             for (int m = 0; m < 2; ++m) { const size_t off = (size_t)(row0 + ai * HALF + (2 * mh + m) * 16) * ldc + col0;
; #pragma unroll
;                 for (int bj = 0; bj < 2; ++bj)
; #pragma unroll
;                     for (int n = 0; n < 2; ++n) bs[m][bj][n] = *(const f32x4*)(base + off + bj * HALF + n * 16); }
.LBB0_1465:
	v_mbcnt_lo_u32_b32 v156, -1, 0
	v_mbcnt_hi_u32_b32 v156, -1, v156
	v_and_b32_e32 v157, 7, v156
	v_bfe_u32 v158, v156, 4, 2
	v_bfe_u32 v160, v156, 3, 1
	v_lshlrev_b32_e32 v157, 13, v157
	v_lshlrev_b32_e32 v160, 6, v160
	v_lshl_add_u32 v160, v158, 4, v160
	v_add_u32_e32 v159, v157, v160
	v_add_u32_e32 v157, 0x10000, v159
	s_lshl_b32 s82, s54, 8
	s_add_i32 s82, s82, s45
	s_lshl_b32 s83, s55, 8
	s_add_i32 s83, s83, s46
	s_lshl_b32 s83, s83, 2
	s_add_u32 s74, s12, s83
	s_addc_u32 s75, s13, 0
	s_lshl_b32 s82, s82, 13
	s_add_u32 s82, s82, s83
	s_add_u32 s76, s6, s82
	s_addc_u32 s77, s7, 0
	s_add_u32 s78, s76, 0x20000
	s_addc_u32 s79, s77, 0
	s_add_u32 s84, s76, 0x40000
	s_addc_u32 s85, s77, 0
	s_add_u32 s86, s76, 0x60000
	s_addc_u32 s87, s77, 0
	s_add_u32 s88, s76, 0x100000
	s_addc_u32 s89, s77, 0
	s_add_u32 s90, s76, 0x120000
	s_addc_u32 s91, s77, 0
	s_add_u32 s94, s76, 0x140000
	s_addc_u32 s95, s77, 0
	s_add_u32 s96, s76, 0x160000
	s_addc_u32 s97, s77, 0
	global_load_dwordx4 v[140:143], v160, s[74:75]
	global_load_dwordx4 v[132:135], v160, s[74:75] offset:512
	global_load_dwordx4 v[166:169], v159, s[76:77]
	global_load_dwordx4 v[170:173], v157, s[76:77]
	global_load_dwordx4 v[174:177], v159, s[76:77] offset:512
	global_load_dwordx4 v[178:181], v157, s[76:77] offset:512
	global_load_dwordx4 v[182:185], v159, s[78:79]
	global_load_dwordx4 v[186:189], v157, s[78:79]
	global_load_dwordx4 v[190:193], v159, s[78:79] offset:512
	global_load_dwordx4 v[194:197], v157, s[78:79] offset:512
	global_load_dwordx4 v[218:221], v159, s[84:85]
	global_load_dwordx4 v[222:225], v157, s[84:85]
	global_load_dwordx4 v[226:229], v159, s[84:85] offset:512
	global_load_dwordx4 v[230:233], v157, s[84:85] offset:512
	global_load_dwordx4 v[234:237], v159, s[86:87]
	global_load_dwordx4 v[238:241], v157, s[86:87]
	global_load_dwordx4 v[242:245], v159, s[86:87] offset:512
	global_load_dwordx4 v[246:249], v157, s[86:87] offset:512
	v_mov_b32_e32 v250, v124
	v_mov_b32_e32 v251, v125
	v_mov_b32_e32 v252, v126
	v_mov_b32_e32 v253, v127
	v_mov_b32_dpp v124, v120 row_ror:8 row_mask:0xf bank_mask:0xc
	v_mov_b32_dpp v125, v121 row_ror:8 row_mask:0xf bank_mask:0xc
	v_mov_b32_dpp v126, v122 row_ror:8 row_mask:0xf bank_mask:0xc
	v_mov_b32_dpp v127, v123 row_ror:8 row_mask:0xf bank_mask:0xc
	v_mov_b32_dpp v120, v250 row_ror:8 row_mask:0xf bank_mask:0x3
	v_mov_b32_dpp v121, v251 row_ror:8 row_mask:0xf bank_mask:0x3
	v_mov_b32_dpp v122, v252 row_ror:8 row_mask:0xf bank_mask:0x3
	v_mov_b32_dpp v123, v253 row_ror:8 row_mask:0xf bank_mask:0x3
	v_mov_b32_e32 v250, v108
	v_mov_b32_e32 v251, v109
	v_mov_b32_e32 v252, v110
	v_mov_b32_e32 v253, v111
	v_mov_b32_dpp v108, v104 row_ror:8 row_mask:0xf bank_mask:0xc
	v_mov_b32_dpp v109, v105 row_ror:8 row_mask:0xf bank_mask:0xc
	v_mov_b32_dpp v110, v106 row_ror:8 row_mask:0xf bank_mask:0xc
	v_mov_b32_dpp v111, v107 row_ror:8 row_mask:0xf bank_mask:0xc
	v_mov_b32_dpp v104, v250 row_ror:8 row_mask:0xf bank_mask:0x3
	v_mov_b32_dpp v105, v251 row_ror:8 row_mask:0xf bank_mask:0x3
	v_mov_b32_dpp v106, v252 row_ror:8 row_mask:0xf bank_mask:0x3
	v_mov_b32_dpp v107, v253 row_ror:8 row_mask:0xf bank_mask:0x3
	v_mov_b32_e32 v250, v116
	v_mov_b32_e32 v251, v117
	v_mov_b32_e32 v252, v118
	v_mov_b32_e32 v253, v119
	v_mov_b32_dpp v116, v112 row_ror:8 row_mask:0xf bank_mask:0xc
	v_mov_b32_dpp v117, v113 row_ror:8 row_mask:0xf bank_mask:0xc
	v_mov_b32_dpp v118, v114 row_ror:8 row_mask:0xf bank_mask:0xc
	v_mov_b32_dpp v119, v115 row_ror:8 row_mask:0xf bank_mask:0xc
	v_mov_b32_dpp v112, v250 row_ror:8 row_mask:0xf bank_mask:0x3
	v_mov_b32_dpp v113, v251 row_ror:8 row_mask:0xf bank_mask:0x3
	v_mov_b32_dpp v114, v252 row_ror:8 row_mask:0xf bank_mask:0x3
	v_mov_b32_dpp v115, v253 row_ror:8 row_mask:0xf bank_mask:0x3
	v_mov_b32_e32 v250, v100
	v_mov_b32_e32 v251, v101
	v_mov_b32_e32 v252, v102
	v_mov_b32_e32 v253, v103
	v_mov_b32_dpp v100, v96 row_ror:8 row_mask:0xf bank_mask:0xc
	v_mov_b32_dpp v101, v97 row_ror:8 row_mask:0xf bank_mask:0xc
	v_mov_b32_dpp v102, v98 row_ror:8 row_mask:0xf bank_mask:0xc
	v_mov_b32_dpp v103, v99 row_ror:8 row_mask:0xf bank_mask:0xc
	v_mov_b32_dpp v96, v250 row_ror:8 row_mask:0xf bank_mask:0x3
	v_mov_b32_dpp v97, v251 row_ror:8 row_mask:0xf bank_mask:0x3
	v_mov_b32_dpp v98, v252 row_ror:8 row_mask:0xf bank_mask:0x3
	v_mov_b32_dpp v99, v253 row_ror:8 row_mask:0xf bank_mask:0x3
	v_mov_b32_e32 v250, v92
	v_mov_b32_e32 v251, v93
	v_mov_b32_e32 v252, v94
	v_mov_b32_e32 v253, v95
	v_mov_b32_dpp v92, v88 row_ror:8 row_mask:0xf bank_mask:0xc
	v_mov_b32_dpp v93, v89 row_ror:8 row_mask:0xf bank_mask:0xc
	v_mov_b32_dpp v94, v90 row_ror:8 row_mask:0xf bank_mask:0xc
	v_mov_b32_dpp v95, v91 row_ror:8 row_mask:0xf bank_mask:0xc
	v_mov_b32_dpp v88, v250 row_ror:8 row_mask:0xf bank_mask:0x3
	v_mov_b32_dpp v89, v251 row_ror:8 row_mask:0xf bank_mask:0x3
	v_mov_b32_dpp v90, v252 row_ror:8 row_mask:0xf bank_mask:0x3
	v_mov_b32_dpp v91, v253 row_ror:8 row_mask:0xf bank_mask:0x3
	v_mov_b32_e32 v250, v76
	v_mov_b32_e32 v251, v77
	v_mov_b32_e32 v252, v78
	v_mov_b32_e32 v253, v79
	v_mov_b32_dpp v76, v72 row_ror:8 row_mask:0xf bank_mask:0xc
	v_mov_b32_dpp v77, v73 row_ror:8 row_mask:0xf bank_mask:0xc
	v_mov_b32_dpp v78, v74 row_ror:8 row_mask:0xf bank_mask:0xc
	v_mov_b32_dpp v79, v75 row_ror:8 row_mask:0xf bank_mask:0xc
	v_mov_b32_dpp v72, v250 row_ror:8 row_mask:0xf bank_mask:0x3
	v_mov_b32_dpp v73, v251 row_ror:8 row_mask:0xf bank_mask:0x3
	v_mov_b32_dpp v74, v252 row_ror:8 row_mask:0xf bank_mask:0x3
	v_mov_b32_dpp v75, v253 row_ror:8 row_mask:0xf bank_mask:0x3
	v_mov_b32_e32 v250, v84
	v_mov_b32_e32 v251, v85
	v_mov_b32_e32 v252, v86
	v_mov_b32_e32 v253, v87
;     __device__ __forceinline__ void operator()(const f32x4 (&acc)[2][2][4][2], const Unit& u, int wr, int wc, int fr_, int fq_) const {
;     ...
;             for (int m = 0; m < 2; ++m) { const int row = row0 + ai * HALF + (2 * mh + m) * 16; const size_t off = (size_t)row * ldc + col0; float ss = 0.f;
; #pragma unroll
;                 for (int bj = 0; bj < 2; ++bj)
; #pragma unroll
;                     for (int n = 0; n < 2; ++n) { const f32x4 o = bs[m][bj][n] + gv[bj][n] * acc[ai][bj][2 * mh + m][n]; *(f32x4*)(out + off + bj * HALF + n * 16) = o;
	v_mov_b32_dpp v84, v80 row_ror:8 row_mask:0xf bank_mask:0xc
	v_mov_b32_dpp v85, v81 row_ror:8 row_mask:0xf bank_mask:0xc
	v_mov_b32_dpp v86, v82 row_ror:8 row_mask:0xf bank_mask:0xc
	v_mov_b32_dpp v87, v83 row_ror:8 row_mask:0xf bank_mask:0xc
	v_mov_b32_dpp v80, v250 row_ror:8 row_mask:0xf bank_mask:0x3
	v_mov_b32_dpp v81, v251 row_ror:8 row_mask:0xf bank_mask:0x3
	v_mov_b32_dpp v82, v252 row_ror:8 row_mask:0xf bank_mask:0x3
	v_mov_b32_dpp v83, v253 row_ror:8 row_mask:0xf bank_mask:0x3
	v_mov_b32_e32 v250, v68
	v_mov_b32_e32 v251, v69
	v_mov_b32_e32 v252, v70
	v_mov_b32_e32 v253, v71
	v_mov_b32_dpp v68, v64 row_ror:8 row_mask:0xf bank_mask:0xc
	v_mov_b32_dpp v69, v65 row_ror:8 row_mask:0xf bank_mask:0xc
	v_mov_b32_dpp v70, v66 row_ror:8 row_mask:0xf bank_mask:0xc
	v_mov_b32_dpp v71, v67 row_ror:8 row_mask:0xf bank_mask:0xc
	v_mov_b32_dpp v64, v250 row_ror:8 row_mask:0xf bank_mask:0x3
	v_mov_b32_dpp v65, v251 row_ror:8 row_mask:0xf bank_mask:0x3
	v_mov_b32_dpp v66, v252 row_ror:8 row_mask:0xf bank_mask:0x3
	v_mov_b32_dpp v67, v253 row_ror:8 row_mask:0xf bank_mask:0x3
	v_mov_b32_e32 v250, v60
	v_mov_b32_e32 v251, v61
	v_mov_b32_e32 v252, v62
	v_mov_b32_e32 v253, v63
	v_mov_b32_dpp v60, v56 row_ror:8 row_mask:0xf bank_mask:0xc
	v_mov_b32_dpp v61, v57 row_ror:8 row_mask:0xf bank_mask:0xc
	v_mov_b32_dpp v62, v58 row_ror:8 row_mask:0xf bank_mask:0xc
	v_mov_b32_dpp v63, v59 row_ror:8 row_mask:0xf bank_mask:0xc
	v_mov_b32_dpp v56, v250 row_ror:8 row_mask:0xf bank_mask:0x3
	v_mov_b32_dpp v57, v251 row_ror:8 row_mask:0xf bank_mask:0x3
	v_mov_b32_dpp v58, v252 row_ror:8 row_mask:0xf bank_mask:0x3
	v_mov_b32_dpp v59, v253 row_ror:8 row_mask:0xf bank_mask:0x3
	v_mov_b32_e32 v250, v44
	v_mov_b32_e32 v251, v45
	v_mov_b32_e32 v252, v46
	v_mov_b32_e32 v253, v47
	v_mov_b32_dpp v44, v40 row_ror:8 row_mask:0xf bank_mask:0xc
	v_mov_b32_dpp v45, v41 row_ror:8 row_mask:0xf bank_mask:0xc
	v_mov_b32_dpp v46, v42 row_ror:8 row_mask:0xf bank_mask:0xc
	v_mov_b32_dpp v47, v43 row_ror:8 row_mask:0xf bank_mask:0xc
	v_mov_b32_dpp v40, v250 row_ror:8 row_mask:0xf bank_mask:0x3
	v_mov_b32_dpp v41, v251 row_ror:8 row_mask:0xf bank_mask:0x3
	v_mov_b32_dpp v42, v252 row_ror:8 row_mask:0xf bank_mask:0x3
	v_mov_b32_dpp v43, v253 row_ror:8 row_mask:0xf bank_mask:0x3
	v_mov_b32_e32 v250, v52
	v_mov_b32_e32 v251, v53
	v_mov_b32_e32 v252, v54
	v_mov_b32_e32 v253, v55
	v_mov_b32_dpp v52, v48 row_ror:8 row_mask:0xf bank_mask:0xc
	v_mov_b32_dpp v53, v49 row_ror:8 row_mask:0xf bank_mask:0xc
	v_mov_b32_dpp v54, v50 row_ror:8 row_mask:0xf bank_mask:0xc
	v_mov_b32_dpp v55, v51 row_ror:8 row_mask:0xf bank_mask:0xc
	v_mov_b32_dpp v48, v250 row_ror:8 row_mask:0xf bank_mask:0x3
	v_mov_b32_dpp v49, v251 row_ror:8 row_mask:0xf bank_mask:0x3
	v_mov_b32_dpp v50, v252 row_ror:8 row_mask:0xf bank_mask:0x3
	v_mov_b32_dpp v51, v253 row_ror:8 row_mask:0xf bank_mask:0x3
	v_mov_b32_e32 v250, v36
	v_mov_b32_e32 v251, v37
	v_mov_b32_e32 v252, v38
	v_mov_b32_e32 v253, v39
	v_mov_b32_dpp v36, v32 row_ror:8 row_mask:0xf bank_mask:0xc
	v_mov_b32_dpp v37, v33 row_ror:8 row_mask:0xf bank_mask:0xc
	v_mov_b32_dpp v38, v34 row_ror:8 row_mask:0xf bank_mask:0xc
	v_mov_b32_dpp v39, v35 row_ror:8 row_mask:0xf bank_mask:0xc
	v_mov_b32_dpp v32, v250 row_ror:8 row_mask:0xf bank_mask:0x3
	v_mov_b32_dpp v33, v251 row_ror:8 row_mask:0xf bank_mask:0x3
	v_mov_b32_dpp v34, v252 row_ror:8 row_mask:0xf bank_mask:0x3
	v_mov_b32_dpp v35, v253 row_ror:8 row_mask:0xf bank_mask:0x3
	v_mov_b32_e32 v250, v28
	v_mov_b32_e32 v251, v29
	v_mov_b32_e32 v252, v30
	v_mov_b32_e32 v253, v31
	v_mov_b32_dpp v28, v24 row_ror:8 row_mask:0xf bank_mask:0xc
	v_mov_b32_dpp v29, v25 row_ror:8 row_mask:0xf bank_mask:0xc
	v_mov_b32_dpp v30, v26 row_ror:8 row_mask:0xf bank_mask:0xc
	v_mov_b32_dpp v31, v27 row_ror:8 row_mask:0xf bank_mask:0xc
	v_mov_b32_dpp v24, v250 row_ror:8 row_mask:0xf bank_mask:0x3
	v_mov_b32_dpp v25, v251 row_ror:8 row_mask:0xf bank_mask:0x3
	v_mov_b32_dpp v26, v252 row_ror:8 row_mask:0xf bank_mask:0x3
	v_mov_b32_dpp v27, v253 row_ror:8 row_mask:0xf bank_mask:0x3
	v_mov_b32_e32 v250, v12
	v_mov_b32_e32 v251, v13
	v_mov_b32_e32 v252, v14
	v_mov_b32_e32 v253, v15
	v_mov_b32_dpp v12, v8 row_ror:8 row_mask:0xf bank_mask:0xc
	v_mov_b32_dpp v13, v9 row_ror:8 row_mask:0xf bank_mask:0xc
	v_mov_b32_dpp v14, v10 row_ror:8 row_mask:0xf bank_mask:0xc
	v_mov_b32_dpp v15, v11 row_ror:8 row_mask:0xf bank_mask:0xc
	v_mov_b32_dpp v8, v250 row_ror:8 row_mask:0xf bank_mask:0x3
	v_mov_b32_dpp v9, v251 row_ror:8 row_mask:0xf bank_mask:0x3
	v_mov_b32_dpp v10, v252 row_ror:8 row_mask:0xf bank_mask:0x3
	v_mov_b32_dpp v11, v253 row_ror:8 row_mask:0xf bank_mask:0x3
	v_mov_b32_e32 v250, v20
	v_mov_b32_e32 v251, v21
	v_mov_b32_e32 v252, v22
	v_mov_b32_e32 v253, v23
	v_mov_b32_dpp v20, v16 row_ror:8 row_mask:0xf bank_mask:0xc
	v_mov_b32_dpp v21, v17 row_ror:8 row_mask:0xf bank_mask:0xc
	v_mov_b32_dpp v22, v18 row_ror:8 row_mask:0xf bank_mask:0xc
	v_mov_b32_dpp v23, v19 row_ror:8 row_mask:0xf bank_mask:0xc
	v_mov_b32_dpp v16, v250 row_ror:8 row_mask:0xf bank_mask:0x3
	v_mov_b32_dpp v17, v251 row_ror:8 row_mask:0xf bank_mask:0x3
	v_mov_b32_dpp v18, v252 row_ror:8 row_mask:0xf bank_mask:0x3
	v_mov_b32_dpp v19, v253 row_ror:8 row_mask:0xf bank_mask:0x3
	v_mov_b32_e32 v250, v4
	v_mov_b32_e32 v251, v5
	v_mov_b32_e32 v252, v6
	v_mov_b32_e32 v253, v7
	v_mov_b32_dpp v4, v0 row_ror:8 row_mask:0xf bank_mask:0xc
	v_mov_b32_dpp v5, v1 row_ror:8 row_mask:0xf bank_mask:0xc
	v_mov_b32_dpp v6, v2 row_ror:8 row_mask:0xf bank_mask:0xc
	v_mov_b32_dpp v7, v3 row_ror:8 row_mask:0xf bank_mask:0xc
	v_mov_b32_dpp v0, v250 row_ror:8 row_mask:0xf bank_mask:0x3
	v_mov_b32_dpp v1, v251 row_ror:8 row_mask:0xf bank_mask:0x3
	v_mov_b32_dpp v2, v252 row_ror:8 row_mask:0xf bank_mask:0x3
	v_mov_b32_dpp v3, v253 row_ror:8 row_mask:0xf bank_mask:0x3
	s_waitcnt vmcnt(8)
;     __device__ __forceinline__ void operator()(const f32x4 (&acc)[2][2][4][2], const Unit& u, int wr, int wc, int fr_, int fq_) const {
;     ...
;             for (int m = 0; m < 2; ++m) { const int row = row0 + ai * HALF + (2 * mh + m) * 16; const size_t off = (size_t)row * ldc + col0; float ss = 0.f;
; #pragma unroll
;                 for (int bj = 0; bj < 2; ++bj)
; #pragma unroll
;                     for (int n = 0; n < 2; ++n) { const f32x4 o = bs[m][bj][n] + gv[bj][n] * acc[ai][bj][2 * mh + m][n]; *(f32x4*)(out + off + bj * HALF + n * 16) = o;
	v_pk_fma_f32 v[126:127], v[126:127], v[142:143], v[168:169]
	v_pk_fma_f32 v[124:125], v[124:125], v[140:141], v[166:167]
	v_pk_fma_f32 v[122:123], v[122:123], v[142:143], v[172:173]
	v_pk_fma_f32 v[120:121], v[120:121], v[140:141], v[170:171]
	v_pk_fma_f32 v[110:111], v[110:111], v[134:135], v[176:177]
	v_pk_fma_f32 v[108:109], v[108:109], v[132:133], v[174:175]
	v_pk_fma_f32 v[106:107], v[106:107], v[134:135], v[180:181]
	v_pk_fma_f32 v[104:105], v[104:105], v[132:133], v[178:179]
	v_pk_fma_f32 v[118:119], v[118:119], v[142:143], v[184:185]
	v_pk_fma_f32 v[116:117], v[116:117], v[140:141], v[182:183]
	v_pk_fma_f32 v[114:115], v[114:115], v[142:143], v[188:189]
	v_pk_fma_f32 v[112:113], v[112:113], v[140:141], v[186:187]
	v_pk_fma_f32 v[102:103], v[102:103], v[134:135], v[192:193]
	v_pk_fma_f32 v[100:101], v[100:101], v[132:133], v[190:191]
	v_pk_fma_f32 v[98:99], v[98:99], v[134:135], v[196:197]
	v_pk_fma_f32 v[96:97], v[96:97], v[132:133], v[194:195]
	global_store_dwordx4 v159, v[124:127], s[76:77]
	global_store_dwordx4 v157, v[120:123], s[76:77]
	global_store_dwordx4 v159, v[108:111], s[76:77] offset:512
	global_store_dwordx4 v157, v[104:107], s[76:77] offset:512
	global_store_dwordx4 v159, v[116:119], s[78:79]
	global_store_dwordx4 v157, v[112:115], s[78:79]
	global_store_dwordx4 v159, v[100:103], s[78:79] offset:512
	global_store_dwordx4 v157, v[96:99], s[78:79] offset:512
	s_nop 1
	global_load_dwordx4 v[166:169], v159, s[88:89]
	global_load_dwordx4 v[170:173], v157, s[88:89]
	global_load_dwordx4 v[174:177], v159, s[88:89] offset:512
	global_load_dwordx4 v[178:181], v157, s[88:89] offset:512
	global_load_dwordx4 v[182:185], v159, s[90:91]
	global_load_dwordx4 v[186:189], v157, s[90:91]
	global_load_dwordx4 v[190:193], v159, s[90:91] offset:512
	global_load_dwordx4 v[194:197], v157, s[90:91] offset:512
	global_load_dwordx4 v[96:99], v159, s[94:95]
	global_load_dwordx4 v[100:103], v157, s[94:95]
	global_load_dwordx4 v[104:107], v159, s[94:95] offset:512
	global_load_dwordx4 v[108:111], v157, s[94:95] offset:512
	global_load_dwordx4 v[112:115], v159, s[96:97]
	global_load_dwordx4 v[116:119], v157, s[96:97]
	global_load_dwordx4 v[120:123], v159, s[96:97] offset:512
	global_load_dwordx4 v[124:127], v157, s[96:97] offset:512
	s_waitcnt vmcnt(24)
	v_pk_fma_f32 v[94:95], v[94:95], v[142:143], v[220:221]
	v_pk_fma_f32 v[92:93], v[92:93], v[140:141], v[218:219]
	v_pk_fma_f32 v[90:91], v[90:91], v[142:143], v[224:225]
	v_pk_fma_f32 v[88:89], v[88:89], v[140:141], v[222:223]
	v_pk_fma_f32 v[78:79], v[78:79], v[134:135], v[228:229]
	v_pk_fma_f32 v[76:77], v[76:77], v[132:133], v[226:227]
	v_pk_fma_f32 v[74:75], v[74:75], v[134:135], v[232:233]
	v_pk_fma_f32 v[72:73], v[72:73], v[132:133], v[230:231]
	v_pk_fma_f32 v[86:87], v[86:87], v[142:143], v[236:237]
	v_pk_fma_f32 v[84:85], v[84:85], v[140:141], v[234:235]
	v_pk_fma_f32 v[82:83], v[82:83], v[142:143], v[240:241]
	v_pk_fma_f32 v[80:81], v[80:81], v[140:141], v[238:239]
	v_pk_fma_f32 v[70:71], v[70:71], v[134:135], v[244:245]
	v_pk_fma_f32 v[68:69], v[68:69], v[132:133], v[242:243]
	v_pk_fma_f32 v[66:67], v[66:67], v[134:135], v[248:249]
	v_pk_fma_f32 v[64:65], v[64:65], v[132:133], v[246:247]
	global_store_dwordx4 v159, v[92:95], s[84:85]
	global_store_dwordx4 v157, v[88:91], s[84:85]
	global_store_dwordx4 v159, v[76:79], s[84:85] offset:512
	global_store_dwordx4 v157, v[72:75], s[84:85] offset:512
	global_store_dwordx4 v159, v[84:87], s[86:87]
	global_store_dwordx4 v157, v[80:83], s[86:87]
	global_store_dwordx4 v159, v[68:71], s[86:87] offset:512
	global_store_dwordx4 v157, v[64:67], s[86:87] offset:512
	s_waitcnt vmcnt(16)
	v_pk_fma_f32 v[62:63], v[62:63], v[142:143], v[168:169]
	v_pk_fma_f32 v[60:61], v[60:61], v[140:141], v[166:167]
	v_pk_fma_f32 v[58:59], v[58:59], v[142:143], v[172:173]
	v_pk_fma_f32 v[56:57], v[56:57], v[140:141], v[170:171]
	v_pk_fma_f32 v[46:47], v[46:47], v[134:135], v[176:177]
	v_pk_fma_f32 v[44:45], v[44:45], v[132:133], v[174:175]
	v_pk_fma_f32 v[42:43], v[42:43], v[134:135], v[180:181]
	v_pk_fma_f32 v[40:41], v[40:41], v[132:133], v[178:179]
	v_pk_fma_f32 v[54:55], v[54:55], v[142:143], v[184:185]
	v_pk_fma_f32 v[52:53], v[52:53], v[140:141], v[182:183]
	v_pk_fma_f32 v[50:51], v[50:51], v[142:143], v[188:189]
	v_pk_fma_f32 v[48:49], v[48:49], v[140:141], v[186:187]
	v_pk_fma_f32 v[38:39], v[38:39], v[134:135], v[192:193]
	v_pk_fma_f32 v[36:37], v[36:37], v[132:133], v[190:191]
	v_pk_fma_f32 v[34:35], v[34:35], v[134:135], v[196:197]
	v_pk_fma_f32 v[32:33], v[32:33], v[132:133], v[194:195]
	global_store_dwordx4 v159, v[60:63], s[88:89]
	global_store_dwordx4 v157, v[56:59], s[88:89]
	global_store_dwordx4 v159, v[44:47], s[88:89] offset:512
	global_store_dwordx4 v157, v[40:43], s[88:89] offset:512
	global_store_dwordx4 v159, v[52:55], s[90:91]
	global_store_dwordx4 v157, v[48:51], s[90:91]
	global_store_dwordx4 v159, v[36:39], s[90:91] offset:512
	global_store_dwordx4 v157, v[32:35], s[90:91] offset:512
	s_waitcnt vmcnt(16)
	v_pk_fma_f32 v[30:31], v[30:31], v[142:143], v[98:99]
	v_pk_fma_f32 v[28:29], v[28:29], v[140:141], v[96:97]
	v_pk_fma_f32 v[26:27], v[26:27], v[142:143], v[102:103]
	v_pk_fma_f32 v[24:25], v[24:25], v[140:141], v[100:101]
	v_pk_fma_f32 v[14:15], v[14:15], v[134:135], v[106:107]
	v_pk_fma_f32 v[12:13], v[12:13], v[132:133], v[104:105]
	v_pk_fma_f32 v[10:11], v[10:11], v[134:135], v[110:111]
	v_pk_fma_f32 v[8:9], v[8:9], v[132:133], v[108:109]
	v_pk_fma_f32 v[22:23], v[22:23], v[142:143], v[114:115]
	v_pk_fma_f32 v[20:21], v[20:21], v[140:141], v[112:113]
	v_pk_fma_f32 v[18:19], v[18:19], v[142:143], v[118:119]
	v_pk_fma_f32 v[16:17], v[16:17], v[140:141], v[116:117]
	v_pk_fma_f32 v[6:7], v[6:7], v[134:135], v[122:123]
	v_pk_fma_f32 v[4:5], v[4:5], v[132:133], v[120:121]
	v_pk_fma_f32 v[2:3], v[2:3], v[134:135], v[126:127]
	v_pk_fma_f32 v[0:1], v[0:1], v[132:133], v[124:125]
	global_store_dwordx4 v159, v[28:31], s[94:95]
	global_store_dwordx4 v157, v[24:27], s[94:95]
	global_store_dwordx4 v159, v[12:15], s[94:95] offset:512
	global_store_dwordx4 v157, v[8:11], s[94:95] offset:512
	global_store_dwordx4 v159, v[20:23], s[96:97]
	global_store_dwordx4 v157, v[16:19], s[96:97]
	global_store_dwordx4 v159, v[4:7], s[96:97] offset:512
	global_store_dwordx4 v157, v[0:3], s[96:97] offset:512
	s_and_b64 vcc, exec, s[0:1]
	s_mov_b64 s[0:1], -1
	s_cbranch_vccnz .LBB0_1450
	s_andn2_b64 vcc, exec, s[10:11]
	s_cbranch_vccnz .LBB0_1449
	s_barrier
	s_branch .LBB0_1449
